# P0 modulation GEMV: 32 w_mod loads in flight per lane (4 trips x 32 k) instead of 8, same FMA order
# speedup vs baseline: 1.0047x; 1.0012x over previous
; __device__ __forceinline__ void p0_phase(ArgP a, LAS unsigned char* lds, int tid, int wave, int lane, int bid, int G) {
;     ...
;     for (int item = bid; item < 576; item += G) {
;         const int l = item / 144, n0 = (item % 144) * 64;
;         const float* wp = a->in[4] + (size_t)l * 1024 * 9216 + n0 + lane;
;         float ac[5] = {0.f, 0.f, 0.f, 0.f, 0.f};
; #pragma unroll 8
;         for (int kk = 0; kk < 128; ++kk) { const int k = wave * 128 + kk; const float wv = wp[(size_t)k * 9216];
; #pragma unroll
;             for (int mi = 0; mi < 5; ++mi) ac[mi] += sl[mi * 1024 + k] * wv; }
.LBB0_1124:
	v_lshl_add_u64 v[74:75], v[8:9], 0, s[2:3]
	global_load_dword v120, v[74:75], off
	v_add_co_u32_e64 v74, s[38:39], s33, v74
	s_nop 1
	v_addc_co_u32_e64 v75, s[38:39], 0, v75, s[38:39]
	global_load_dword v122, v[74:75], off
	v_add_co_u32_e64 v74, s[38:39], s33, v74
	s_nop 1
	v_addc_co_u32_e64 v75, s[38:39], 0, v75, s[38:39]
	global_load_dword v124, v[74:75], off
	v_add_co_u32_e64 v74, s[38:39], s33, v74
	s_nop 1
	v_addc_co_u32_e64 v75, s[38:39], 0, v75, s[38:39]
	global_load_dword v126, v[74:75], off
	v_add_co_u32_e64 v74, s[38:39], s33, v74
	s_nop 1
	v_addc_co_u32_e64 v75, s[38:39], 0, v75, s[38:39]
	global_load_dword v128, v[74:75], off
	v_add_co_u32_e64 v74, s[38:39], s33, v74
	s_nop 1
	v_addc_co_u32_e64 v75, s[38:39], 0, v75, s[38:39]
	global_load_dword v130, v[74:75], off
	v_add_co_u32_e64 v74, s[38:39], s33, v74
	s_nop 1
	v_addc_co_u32_e64 v75, s[38:39], 0, v75, s[38:39]
	global_load_dword v132, v[74:75], off
	v_add_co_u32_e64 v74, s[38:39], s33, v74
	s_nop 1
	v_addc_co_u32_e64 v75, s[38:39], 0, v75, s[38:39]
	global_load_dword v134, v[74:75], off
	v_add_co_u32_e64 v74, s[38:39], s33, v74
	s_nop 1
	v_addc_co_u32_e64 v75, s[38:39], 0, v75, s[38:39]
	global_load_dword v136, v[74:75], off
	v_add_co_u32_e64 v74, s[38:39], s33, v74
	s_nop 1
	v_addc_co_u32_e64 v75, s[38:39], 0, v75, s[38:39]
	global_load_dword v138, v[74:75], off
	v_add_co_u32_e64 v74, s[38:39], s33, v74
	s_nop 1
	v_addc_co_u32_e64 v75, s[38:39], 0, v75, s[38:39]
	global_load_dword v140, v[74:75], off
	v_add_co_u32_e64 v74, s[38:39], s33, v74
	s_nop 1
	v_addc_co_u32_e64 v75, s[38:39], 0, v75, s[38:39]
	global_load_dword v142, v[74:75], off
	v_add_co_u32_e64 v74, s[38:39], s33, v74
	s_nop 1
	v_addc_co_u32_e64 v75, s[38:39], 0, v75, s[38:39]
	global_load_dword v144, v[74:75], off
	v_add_co_u32_e64 v74, s[38:39], s33, v74
	s_nop 1
	v_addc_co_u32_e64 v75, s[38:39], 0, v75, s[38:39]
	global_load_dword v146, v[74:75], off
	v_add_co_u32_e64 v74, s[38:39], s33, v74
	s_nop 1
	v_addc_co_u32_e64 v75, s[38:39], 0, v75, s[38:39]
	global_load_dword v148, v[74:75], off
	v_add_co_u32_e64 v74, s[38:39], s33, v74
	s_nop 1
	v_addc_co_u32_e64 v75, s[38:39], 0, v75, s[38:39]
	global_load_dword v150, v[74:75], off
	v_add_co_u32_e64 v74, s[38:39], s33, v74
	s_nop 1
	v_addc_co_u32_e64 v75, s[38:39], 0, v75, s[38:39]
	global_load_dword v152, v[74:75], off
	v_add_co_u32_e64 v74, s[38:39], s33, v74
	s_nop 1
	v_addc_co_u32_e64 v75, s[38:39], 0, v75, s[38:39]
	global_load_dword v154, v[74:75], off
	v_add_co_u32_e64 v74, s[38:39], s33, v74
	s_nop 1
	v_addc_co_u32_e64 v75, s[38:39], 0, v75, s[38:39]
	global_load_dword v156, v[74:75], off
	v_add_co_u32_e64 v74, s[38:39], s33, v74
	s_nop 1
	v_addc_co_u32_e64 v75, s[38:39], 0, v75, s[38:39]
	global_load_dword v158, v[74:75], off
	v_add_co_u32_e64 v74, s[38:39], s33, v74
	s_nop 1
	v_addc_co_u32_e64 v75, s[38:39], 0, v75, s[38:39]
	global_load_dword v160, v[74:75], off
	v_add_co_u32_e64 v74, s[38:39], s33, v74
	s_nop 1
	v_addc_co_u32_e64 v75, s[38:39], 0, v75, s[38:39]
	global_load_dword v162, v[74:75], off
	v_add_co_u32_e64 v74, s[38:39], s33, v74
	s_nop 1
	v_addc_co_u32_e64 v75, s[38:39], 0, v75, s[38:39]
	global_load_dword v164, v[74:75], off
	v_add_co_u32_e64 v74, s[38:39], s33, v74
	s_nop 1
	v_addc_co_u32_e64 v75, s[38:39], 0, v75, s[38:39]
	global_load_dword v166, v[74:75], off
	v_add_co_u32_e64 v74, s[38:39], s33, v74
	s_nop 1
	v_addc_co_u32_e64 v75, s[38:39], 0, v75, s[38:39]
	global_load_dword v168, v[74:75], off
	v_add_co_u32_e64 v74, s[38:39], s33, v74
	s_nop 1
	v_addc_co_u32_e64 v75, s[38:39], 0, v75, s[38:39]
	global_load_dword v170, v[74:75], off
	v_add_co_u32_e64 v74, s[38:39], s33, v74
	s_nop 1
	v_addc_co_u32_e64 v75, s[38:39], 0, v75, s[38:39]
	global_load_dword v172, v[74:75], off
	v_add_co_u32_e64 v74, s[38:39], s33, v74
	s_nop 1
	v_addc_co_u32_e64 v75, s[38:39], 0, v75, s[38:39]
	global_load_dword v174, v[74:75], off
	v_add_co_u32_e64 v74, s[38:39], s33, v74
	s_nop 1
	v_addc_co_u32_e64 v75, s[38:39], 0, v75, s[38:39]
	global_load_dword v176, v[74:75], off
	v_add_co_u32_e64 v74, s[38:39], s33, v74
	s_nop 1
	v_addc_co_u32_e64 v75, s[38:39], 0, v75, s[38:39]
	global_load_dword v178, v[74:75], off
	v_add_co_u32_e64 v74, s[38:39], s33, v74
	s_nop 1
	v_addc_co_u32_e64 v75, s[38:39], 0, v75, s[38:39]
	global_load_dword v180, v[74:75], off
	v_add_co_u32_e64 v74, s[38:39], s33, v74
	s_nop 1
	v_addc_co_u32_e64 v75, s[38:39], 0, v75, s[38:39]
	global_load_dword v182, v[74:75], off
	v_mov_b32_e32 v15, s13
	ds_read_b128 v[16:19], v15
	ds_read_b128 v[20:23], v15 offset:16
	ds_read_b128 v[24:27], v15 offset:4096
	ds_read_b128 v[28:31], v15 offset:4112
	ds_read_b128 v[32:35], v15 offset:8192
	ds_read_b128 v[36:39], v15 offset:8208
	ds_read_b128 v[40:43], v15 offset:12288
	ds_read_b128 v[44:47], v15 offset:12304
	ds_read_b128 v[48:51], v15 offset:16384
	ds_read_b128 v[52:55], v15 offset:16400
	s_waitcnt lgkmcnt(0)
	v_mov_b32_e32 v72, v16
	v_mov_b32_e32 v73, v24
	v_mov_b32_e32 v24, v17
	v_mov_b32_e32 v16, v18
	v_mov_b32_e32 v17, v26
	v_mov_b32_e32 v26, v19
	v_mov_b32_e32 v18, v32
	v_mov_b32_e32 v19, v40
	v_mov_b32_e32 v40, v33
	v_mov_b32_e32 v32, v34
	v_mov_b32_e32 v33, v42
	v_mov_b32_e32 v42, v35
	v_mov_b32_e32 v34, v20
	v_mov_b32_e32 v35, v28
	v_mov_b32_e32 v28, v21
	v_mov_b32_e32 v20, v22
	v_mov_b32_e32 v21, v30
	v_mov_b32_e32 v30, v23
	v_mov_b32_e32 v22, v36
	v_mov_b32_e32 v23, v44
	v_mov_b32_e32 v44, v37
	v_mov_b32_e32 v36, v38
	v_mov_b32_e32 v37, v46
	v_mov_b32_e32 v46, v39
	s_waitcnt vmcnt(31)
	v_pk_fma_f32 v[10:11], v[120:121], v[72:73], v[10:11] op_sel_hi:[0,1,1]
	v_pk_fma_f32 v[12:13], v[120:121], v[18:19], v[12:13] op_sel_hi:[0,1,1]
	v_fmac_f32_e32 v14, v120, v48
	s_waitcnt vmcnt(30)
; __device__ __forceinline__ void p0_phase(ArgP a, LAS unsigned char* lds, int tid, int wave, int lane, int bid, int G) {
;     ...
;         for (int kk = 0; kk < 128; ++kk) { const int k = wave * 128 + kk; const float wv = wp[(size_t)k * 9216];
; #pragma unroll
;             for (int mi = 0; mi < 5; ++mi) ac[mi] += sl[mi * 1024 + k] * wv; }
	v_pk_fma_f32 v[10:11], v[122:123], v[24:25], v[10:11] op_sel_hi:[0,1,1]
	v_pk_fma_f32 v[12:13], v[122:123], v[40:41], v[12:13] op_sel_hi:[0,1,1]
	v_fmac_f32_e32 v14, v122, v49
	s_waitcnt vmcnt(29)
	v_pk_fma_f32 v[10:11], v[124:125], v[16:17], v[10:11] op_sel_hi:[0,1,1]
	v_pk_fma_f32 v[12:13], v[124:125], v[32:33], v[12:13] op_sel_hi:[0,1,1]
	v_fmac_f32_e32 v14, v124, v50
	s_waitcnt vmcnt(28)
	v_pk_fma_f32 v[10:11], v[126:127], v[26:27], v[10:11] op_sel_hi:[0,1,1]
	v_pk_fma_f32 v[12:13], v[126:127], v[42:43], v[12:13] op_sel_hi:[0,1,1]
	v_fmac_f32_e32 v14, v126, v51
	s_waitcnt vmcnt(27)
	v_pk_fma_f32 v[10:11], v[128:129], v[34:35], v[10:11] op_sel_hi:[0,1,1]
	v_pk_fma_f32 v[12:13], v[128:129], v[22:23], v[12:13] op_sel_hi:[0,1,1]
	v_fmac_f32_e32 v14, v128, v52
	s_waitcnt vmcnt(26)
	v_pk_fma_f32 v[10:11], v[130:131], v[28:29], v[10:11] op_sel_hi:[0,1,1]
	v_pk_fma_f32 v[12:13], v[130:131], v[44:45], v[12:13] op_sel_hi:[0,1,1]
	v_fmac_f32_e32 v14, v130, v53
	s_waitcnt vmcnt(25)
	v_pk_fma_f32 v[10:11], v[132:133], v[20:21], v[10:11] op_sel_hi:[0,1,1]
	v_pk_fma_f32 v[12:13], v[132:133], v[36:37], v[12:13] op_sel_hi:[0,1,1]
	v_fmac_f32_e32 v14, v132, v54
	s_waitcnt vmcnt(24)
	v_pk_fma_f32 v[10:11], v[134:135], v[30:31], v[10:11] op_sel_hi:[0,1,1]
	v_pk_fma_f32 v[12:13], v[134:135], v[46:47], v[12:13] op_sel_hi:[0,1,1]
	v_fmac_f32_e32 v14, v134, v55
	ds_read_b128 v[16:19], v15 offset:32
	ds_read_b128 v[20:23], v15 offset:48
	ds_read_b128 v[24:27], v15 offset:4128
	ds_read_b128 v[28:31], v15 offset:4144
	ds_read_b128 v[32:35], v15 offset:8224
	ds_read_b128 v[36:39], v15 offset:8240
	ds_read_b128 v[40:43], v15 offset:12320
	ds_read_b128 v[44:47], v15 offset:12336
	ds_read_b128 v[48:51], v15 offset:16416
	ds_read_b128 v[52:55], v15 offset:16432
	s_waitcnt lgkmcnt(0)
	v_mov_b32_e32 v72, v16
	v_mov_b32_e32 v73, v24
	v_mov_b32_e32 v24, v17
	v_mov_b32_e32 v16, v18
	v_mov_b32_e32 v17, v26
	v_mov_b32_e32 v26, v19
	v_mov_b32_e32 v18, v32
	v_mov_b32_e32 v19, v40
	v_mov_b32_e32 v40, v33
	v_mov_b32_e32 v32, v34
	v_mov_b32_e32 v33, v42
	v_mov_b32_e32 v42, v35
	v_mov_b32_e32 v34, v20
	v_mov_b32_e32 v35, v28
	v_mov_b32_e32 v28, v21
	v_mov_b32_e32 v20, v22
	v_mov_b32_e32 v21, v30
	v_mov_b32_e32 v30, v23
	v_mov_b32_e32 v22, v36
	v_mov_b32_e32 v23, v44
	v_mov_b32_e32 v44, v37
	v_mov_b32_e32 v36, v38
	v_mov_b32_e32 v37, v46
	v_mov_b32_e32 v46, v39
	s_waitcnt vmcnt(23)
	v_pk_fma_f32 v[10:11], v[136:137], v[72:73], v[10:11] op_sel_hi:[0,1,1]
	v_pk_fma_f32 v[12:13], v[136:137], v[18:19], v[12:13] op_sel_hi:[0,1,1]
	v_fmac_f32_e32 v14, v136, v48
	s_waitcnt vmcnt(22)
	v_pk_fma_f32 v[10:11], v[138:139], v[24:25], v[10:11] op_sel_hi:[0,1,1]
	v_pk_fma_f32 v[12:13], v[138:139], v[40:41], v[12:13] op_sel_hi:[0,1,1]
	v_fmac_f32_e32 v14, v138, v49
	s_waitcnt vmcnt(21)
	v_pk_fma_f32 v[10:11], v[140:141], v[16:17], v[10:11] op_sel_hi:[0,1,1]
	v_pk_fma_f32 v[12:13], v[140:141], v[32:33], v[12:13] op_sel_hi:[0,1,1]
	v_fmac_f32_e32 v14, v140, v50
	s_waitcnt vmcnt(20)
	v_pk_fma_f32 v[10:11], v[142:143], v[26:27], v[10:11] op_sel_hi:[0,1,1]
	v_pk_fma_f32 v[12:13], v[142:143], v[42:43], v[12:13] op_sel_hi:[0,1,1]
	v_fmac_f32_e32 v14, v142, v51
	s_waitcnt vmcnt(19)
	v_pk_fma_f32 v[10:11], v[144:145], v[34:35], v[10:11] op_sel_hi:[0,1,1]
	v_pk_fma_f32 v[12:13], v[144:145], v[22:23], v[12:13] op_sel_hi:[0,1,1]
	v_fmac_f32_e32 v14, v144, v52
	s_waitcnt vmcnt(18)
	v_pk_fma_f32 v[10:11], v[146:147], v[28:29], v[10:11] op_sel_hi:[0,1,1]
	v_pk_fma_f32 v[12:13], v[146:147], v[44:45], v[12:13] op_sel_hi:[0,1,1]
	v_fmac_f32_e32 v14, v146, v53
	s_waitcnt vmcnt(17)
	v_pk_fma_f32 v[10:11], v[148:149], v[20:21], v[10:11] op_sel_hi:[0,1,1]
	v_pk_fma_f32 v[12:13], v[148:149], v[36:37], v[12:13] op_sel_hi:[0,1,1]
	v_fmac_f32_e32 v14, v148, v54
	s_waitcnt vmcnt(16)
	v_pk_fma_f32 v[10:11], v[150:151], v[30:31], v[10:11] op_sel_hi:[0,1,1]
	v_pk_fma_f32 v[12:13], v[150:151], v[46:47], v[12:13] op_sel_hi:[0,1,1]
	v_fmac_f32_e32 v14, v150, v55
	ds_read_b128 v[16:19], v15 offset:64
	ds_read_b128 v[20:23], v15 offset:80
	ds_read_b128 v[24:27], v15 offset:4160
	ds_read_b128 v[28:31], v15 offset:4176
	ds_read_b128 v[32:35], v15 offset:8256
	ds_read_b128 v[36:39], v15 offset:8272
	ds_read_b128 v[40:43], v15 offset:12352
	ds_read_b128 v[44:47], v15 offset:12368
	ds_read_b128 v[48:51], v15 offset:16448
	ds_read_b128 v[52:55], v15 offset:16464
	s_waitcnt lgkmcnt(0)
	v_mov_b32_e32 v72, v16
	v_mov_b32_e32 v73, v24
	v_mov_b32_e32 v24, v17
	v_mov_b32_e32 v16, v18
	v_mov_b32_e32 v17, v26
	v_mov_b32_e32 v26, v19
	v_mov_b32_e32 v18, v32
	v_mov_b32_e32 v19, v40
	v_mov_b32_e32 v40, v33
	v_mov_b32_e32 v32, v34
	v_mov_b32_e32 v33, v42
	v_mov_b32_e32 v42, v35
	v_mov_b32_e32 v34, v20
	v_mov_b32_e32 v35, v28
	v_mov_b32_e32 v28, v21
	v_mov_b32_e32 v20, v22
	v_mov_b32_e32 v21, v30
	v_mov_b32_e32 v30, v23
	v_mov_b32_e32 v22, v36
	v_mov_b32_e32 v23, v44
	v_mov_b32_e32 v44, v37
	v_mov_b32_e32 v36, v38
	v_mov_b32_e32 v37, v46
	v_mov_b32_e32 v46, v39
	s_waitcnt vmcnt(15)
	v_pk_fma_f32 v[10:11], v[152:153], v[72:73], v[10:11] op_sel_hi:[0,1,1]
	v_pk_fma_f32 v[12:13], v[152:153], v[18:19], v[12:13] op_sel_hi:[0,1,1]
	v_fmac_f32_e32 v14, v152, v48
	s_waitcnt vmcnt(14)
	v_pk_fma_f32 v[10:11], v[154:155], v[24:25], v[10:11] op_sel_hi:[0,1,1]
	v_pk_fma_f32 v[12:13], v[154:155], v[40:41], v[12:13] op_sel_hi:[0,1,1]
	v_fmac_f32_e32 v14, v154, v49
	s_waitcnt vmcnt(13)
; __device__ __forceinline__ void p0_phase(ArgP a, LAS unsigned char* lds, int tid, int wave, int lane, int bid, int G) {
;     ...
;         for (int kk = 0; kk < 128; ++kk) { const int k = wave * 128 + kk; const float wv = wp[(size_t)k * 9216];
; #pragma unroll
;             for (int mi = 0; mi < 5; ++mi) ac[mi] += sl[mi * 1024 + k] * wv; }
; #pragma unroll
;         for (int mi = 0; mi < 5; ++mi) red[(wave * 5 + mi) * 64 + lane] = ac[mi];
;         __syncthreads();
;         if (tid < 320) { const int mi = tid >> 6; float s = 0.f;
; #pragma unroll
;             for (int w = 0; w < 8; ++w) s += red[(w * 5 + mi) * 64 + lane];
;             MOD[(size_t)(l * 5 + mi) * 9216 + n0 + lane] = s + a->in[5][l * 9216 + n0 + lane]; }
	v_pk_fma_f32 v[10:11], v[156:157], v[16:17], v[10:11] op_sel_hi:[0,1,1]
	v_pk_fma_f32 v[12:13], v[156:157], v[32:33], v[12:13] op_sel_hi:[0,1,1]
	v_fmac_f32_e32 v14, v156, v50
	s_waitcnt vmcnt(12)
	v_pk_fma_f32 v[10:11], v[158:159], v[26:27], v[10:11] op_sel_hi:[0,1,1]
	v_pk_fma_f32 v[12:13], v[158:159], v[42:43], v[12:13] op_sel_hi:[0,1,1]
	v_fmac_f32_e32 v14, v158, v51
	s_waitcnt vmcnt(11)
	v_pk_fma_f32 v[10:11], v[160:161], v[34:35], v[10:11] op_sel_hi:[0,1,1]
	v_pk_fma_f32 v[12:13], v[160:161], v[22:23], v[12:13] op_sel_hi:[0,1,1]
	v_fmac_f32_e32 v14, v160, v52
	s_waitcnt vmcnt(10)
	v_pk_fma_f32 v[10:11], v[162:163], v[28:29], v[10:11] op_sel_hi:[0,1,1]
	v_pk_fma_f32 v[12:13], v[162:163], v[44:45], v[12:13] op_sel_hi:[0,1,1]
	v_fmac_f32_e32 v14, v162, v53
	s_waitcnt vmcnt(9)
	v_pk_fma_f32 v[10:11], v[164:165], v[20:21], v[10:11] op_sel_hi:[0,1,1]
	v_pk_fma_f32 v[12:13], v[164:165], v[36:37], v[12:13] op_sel_hi:[0,1,1]
	v_fmac_f32_e32 v14, v164, v54
	s_waitcnt vmcnt(8)
	v_pk_fma_f32 v[10:11], v[166:167], v[30:31], v[10:11] op_sel_hi:[0,1,1]
	v_pk_fma_f32 v[12:13], v[166:167], v[46:47], v[12:13] op_sel_hi:[0,1,1]
	v_fmac_f32_e32 v14, v166, v55
	ds_read_b128 v[16:19], v15 offset:96
	ds_read_b128 v[20:23], v15 offset:112
	ds_read_b128 v[24:27], v15 offset:4192
	ds_read_b128 v[28:31], v15 offset:4208
	ds_read_b128 v[32:35], v15 offset:8288
	ds_read_b128 v[36:39], v15 offset:8304
	ds_read_b128 v[40:43], v15 offset:12384
	ds_read_b128 v[44:47], v15 offset:12400
	ds_read_b128 v[48:51], v15 offset:16480
	ds_read_b128 v[52:55], v15 offset:16496
	s_waitcnt lgkmcnt(0)
	v_mov_b32_e32 v72, v16
	v_mov_b32_e32 v73, v24
	v_mov_b32_e32 v24, v17
	v_mov_b32_e32 v16, v18
	v_mov_b32_e32 v17, v26
	v_mov_b32_e32 v26, v19
	v_mov_b32_e32 v18, v32
	v_mov_b32_e32 v19, v40
	v_mov_b32_e32 v40, v33
	v_mov_b32_e32 v32, v34
	v_mov_b32_e32 v33, v42
	v_mov_b32_e32 v42, v35
	v_mov_b32_e32 v34, v20
	v_mov_b32_e32 v35, v28
	v_mov_b32_e32 v28, v21
	v_mov_b32_e32 v20, v22
	v_mov_b32_e32 v21, v30
	v_mov_b32_e32 v30, v23
	v_mov_b32_e32 v22, v36
	v_mov_b32_e32 v23, v44
	v_mov_b32_e32 v44, v37
	v_mov_b32_e32 v36, v38
	v_mov_b32_e32 v37, v46
	v_mov_b32_e32 v46, v39
	s_waitcnt vmcnt(7)
	v_pk_fma_f32 v[10:11], v[168:169], v[72:73], v[10:11] op_sel_hi:[0,1,1]
	v_pk_fma_f32 v[12:13], v[168:169], v[18:19], v[12:13] op_sel_hi:[0,1,1]
	v_fmac_f32_e32 v14, v168, v48
	s_waitcnt vmcnt(6)
	v_pk_fma_f32 v[10:11], v[170:171], v[24:25], v[10:11] op_sel_hi:[0,1,1]
	v_pk_fma_f32 v[12:13], v[170:171], v[40:41], v[12:13] op_sel_hi:[0,1,1]
	v_fmac_f32_e32 v14, v170, v49
	s_waitcnt vmcnt(5)
	v_pk_fma_f32 v[10:11], v[172:173], v[16:17], v[10:11] op_sel_hi:[0,1,1]
	v_pk_fma_f32 v[12:13], v[172:173], v[32:33], v[12:13] op_sel_hi:[0,1,1]
	v_fmac_f32_e32 v14, v172, v50
	s_waitcnt vmcnt(4)
	v_pk_fma_f32 v[10:11], v[174:175], v[26:27], v[10:11] op_sel_hi:[0,1,1]
	v_pk_fma_f32 v[12:13], v[174:175], v[42:43], v[12:13] op_sel_hi:[0,1,1]
	v_fmac_f32_e32 v14, v174, v51
	s_waitcnt vmcnt(3)
	v_pk_fma_f32 v[10:11], v[176:177], v[34:35], v[10:11] op_sel_hi:[0,1,1]
	v_pk_fma_f32 v[12:13], v[176:177], v[22:23], v[12:13] op_sel_hi:[0,1,1]
	v_fmac_f32_e32 v14, v176, v52
	s_waitcnt vmcnt(2)
	v_pk_fma_f32 v[10:11], v[178:179], v[28:29], v[10:11] op_sel_hi:[0,1,1]
	v_pk_fma_f32 v[12:13], v[178:179], v[44:45], v[12:13] op_sel_hi:[0,1,1]
	v_fmac_f32_e32 v14, v178, v53
	s_waitcnt vmcnt(1)
	v_pk_fma_f32 v[10:11], v[180:181], v[20:21], v[10:11] op_sel_hi:[0,1,1]
	v_pk_fma_f32 v[12:13], v[180:181], v[36:37], v[12:13] op_sel_hi:[0,1,1]
	v_fmac_f32_e32 v14, v180, v54
	s_waitcnt vmcnt(0)
	v_pk_fma_f32 v[10:11], v[182:183], v[30:31], v[10:11] op_sel_hi:[0,1,1]
	v_pk_fma_f32 v[12:13], v[182:183], v[46:47], v[12:13] op_sel_hi:[0,1,1]
	v_fmac_f32_e32 v14, v182, v55
	s_add_u32 s2, s2, 0x120000
	s_addc_u32 s3, s3, 0
	s_addk_i32 s13, 0x80
	s_cmp_eq_u32 s2, 0x480000
	s_cbranch_scc0 .LBB0_1124
	v_add_u32_e32 v8, s8, v1
	ds_write2st64_b32 v8, v10, v11 offset0:80 offset1:81
	ds_write2st64_b32 v8, v12, v13 offset0:82 offset1:83
	ds_write_b32 v8, v14 offset:21504
	s_waitcnt lgkmcnt(0)
	s_barrier
	s_and_saveexec_b64 s[2:3], vcc
	s_cbranch_execz .LBB0_1122
	s_load_dwordx2 s[14:15], s[30:31], 0x28
	s_mul_i32 s13, s12, 0x2400
	s_add_i32 s13, s13, s0
	v_add_u32_e32 v8, s13, v2
	v_ashrrev_i32_e32 v9, 31, v8
	s_waitcnt lgkmcnt(0)
	v_lshl_add_u64 v[8:9], v[8:9], 2, s[14:15]
	global_load_dword v20, v[8:9], off
	ds_read2st64_b32 v[8:9], v5 offset0:80 offset1:85
	ds_read2st64_b32 v[10:11], v5 offset0:90 offset1:95
	ds_read2st64_b32 v[12:13], v5 offset0:100 offset1:105
	ds_read2st64_b32 v[14:15], v5 offset0:110 offset1:115
	v_mad_u64_u32 v[16:17], s[12:13], s12, 5, v[4:5]
	s_waitcnt lgkmcnt(3)
	v_add_f32_e32 v8, 0, v8
	v_add_f32_e32 v8, v8, v9
	s_waitcnt lgkmcnt(2)
	v_add_f32_e32 v8, v8, v10
	v_add_f32_e32 v8, v8, v11
	s_waitcnt lgkmcnt(1)
	v_add_f32_e32 v8, v8, v12
	v_mov_b64_e32 v[18:19], s[10:11]
	v_add_f32_e32 v8, v8, v13
	v_mad_i64_i32 v[16:17], s[12:13], v16, s33, v[18:19]
	s_waitcnt lgkmcnt(0)
	v_add_f32_e32 v8, v8, v14
	v_lshl_add_u64 v[16:17], s[0:1], 2, v[16:17]
	v_add_f32_e32 v8, v8, v15
	s_waitcnt vmcnt(0)
	v_add_f32_e32 v10, v8, v20
	v_lshl_add_u64 v[8:9], v[2:3], 2, v[16:17]
	global_store_dword v[8:9], v10, off
	s_branch .LBB0_1122
